# phase 0: conditioning staging loads batched (36 in flight) and hand-written modulation GEMV K loop (32 row loads in flight), on top of the XCD-local NA order
# baseline (speedup 1.0000x reference)
; __device__ __forceinline__ void phase0(const Params& p, char* shm) {
;     ...
;     if (task < N_GEMV) {
;       float* condS = fs;
;       float* red = fs + 9 * 2048;
;       if (!cond_ready) {
;         for (int i = tid; i < 9 * 2048; i += 512) { const int r = i >> 11, k = i & 2047; const float v = r < 8 ? p.in[1][r * 2048 + k] : p.in[3][k]; condS[i] = v / (1.f + __expf(-v)); }
;         cond_ready = true;
;         __syncthreads();
.LBB0_112:
	s_xor_b64 s[0:1], s[54:55], -1
	s_andn2_b64 vcc, exec, s[0:1]
	s_cbranch_vccnz .LBB0_117
	s_and_saveexec_b64 s[20:21], s[10:11]
	s_cbranch_execz .LBB0_116
	s_mov_b64 s[22:23], 0
	v_mov_b64_e32 v[2:3], v[86:87]
	v_mov_b32_e32 v4, v73
	v_mov_b32_e32 v5, v42
	global_load_dword v182, v[2:3], off
	v_lshl_add_u64 v[2:3], v[2:3], 0, s[50:51]
	global_load_dword v183, v[2:3], off
	v_lshl_add_u64 v[2:3], v[2:3], 0, s[50:51]
	global_load_dword v184, v[2:3], off
	v_lshl_add_u64 v[2:3], v[2:3], 0, s[50:51]
	global_load_dword v185, v[2:3], off
	v_lshl_add_u64 v[2:3], v[2:3], 0, s[50:51]
	global_load_dword v186, v[2:3], off
	v_lshl_add_u64 v[2:3], v[2:3], 0, s[50:51]
	global_load_dword v187, v[2:3], off
	v_lshl_add_u64 v[2:3], v[2:3], 0, s[50:51]
	global_load_dword v188, v[2:3], off
	v_lshl_add_u64 v[2:3], v[2:3], 0, s[50:51]
	global_load_dword v189, v[2:3], off
	v_lshl_add_u64 v[2:3], v[2:3], 0, s[50:51]
	global_load_dword v190, v[2:3], off
	v_lshl_add_u64 v[2:3], v[2:3], 0, s[50:51]
	global_load_dword v191, v[2:3], off
	v_lshl_add_u64 v[2:3], v[2:3], 0, s[50:51]
	global_load_dword v192, v[2:3], off
	v_lshl_add_u64 v[2:3], v[2:3], 0, s[50:51]
	global_load_dword v193, v[2:3], off
	v_lshl_add_u64 v[2:3], v[2:3], 0, s[50:51]
	global_load_dword v194, v[2:3], off
	v_lshl_add_u64 v[2:3], v[2:3], 0, s[50:51]
	global_load_dword v195, v[2:3], off
	v_lshl_add_u64 v[2:3], v[2:3], 0, s[50:51]
	global_load_dword v196, v[2:3], off
	v_lshl_add_u64 v[2:3], v[2:3], 0, s[50:51]
	global_load_dword v197, v[2:3], off
	v_lshl_add_u64 v[2:3], v[2:3], 0, s[50:51]
	global_load_dword v198, v[2:3], off
	v_lshl_add_u64 v[2:3], v[2:3], 0, s[50:51]
	global_load_dword v199, v[2:3], off
	v_lshl_add_u64 v[2:3], v[2:3], 0, s[50:51]
	global_load_dword v200, v[2:3], off
	v_lshl_add_u64 v[2:3], v[2:3], 0, s[50:51]
	global_load_dword v201, v[2:3], off
	v_lshl_add_u64 v[2:3], v[2:3], 0, s[50:51]
	global_load_dword v202, v[2:3], off
	v_lshl_add_u64 v[2:3], v[2:3], 0, s[50:51]
	global_load_dword v203, v[2:3], off
	v_lshl_add_u64 v[2:3], v[2:3], 0, s[50:51]
	global_load_dword v204, v[2:3], off
	v_lshl_add_u64 v[2:3], v[2:3], 0, s[50:51]
	global_load_dword v205, v[2:3], off
	v_lshl_add_u64 v[2:3], v[2:3], 0, s[50:51]
	global_load_dword v206, v[2:3], off
	v_lshl_add_u64 v[2:3], v[2:3], 0, s[50:51]
	global_load_dword v207, v[2:3], off
	v_lshl_add_u64 v[2:3], v[2:3], 0, s[50:51]
	global_load_dword v208, v[2:3], off
	v_lshl_add_u64 v[2:3], v[2:3], 0, s[50:51]
	global_load_dword v209, v[2:3], off
	v_lshl_add_u64 v[2:3], v[2:3], 0, s[50:51]
	global_load_dword v210, v[2:3], off
	v_lshl_add_u64 v[2:3], v[2:3], 0, s[50:51]
	global_load_dword v211, v[2:3], off
	v_lshl_add_u64 v[2:3], v[2:3], 0, s[50:51]
	global_load_dword v212, v[2:3], off
	v_lshl_add_u64 v[2:3], v[2:3], 0, s[50:51]
	global_load_dword v213, v[2:3], off
	v_lshl_add_u64 v[2:3], v[2:3], 0, s[50:51]
	v_lshlrev_b32_e32 v46, 2, v5
	v_lshl_add_u64 v[2:3], s[28:29], 0, v[46:47]
	global_load_dword v214, v[2:3], off
	v_lshl_add_u64 v[2:3], v[2:3], 0, s[50:51]
	global_load_dword v215, v[2:3], off
	v_lshl_add_u64 v[2:3], v[2:3], 0, s[50:51]
	global_load_dword v216, v[2:3], off
	v_lshl_add_u64 v[2:3], v[2:3], 0, s[50:51]
	global_load_dword v217, v[2:3], off
	v_lshl_add_u64 v[2:3], v[2:3], 0, s[50:51]
	s_waitcnt vmcnt(35)
	v_mov_b32_e32 v6, v182
	v_mul_f32_e32 v7, 0xbfb8aa3b, v6
	v_exp_f32_e32 v7, v7
	s_nop 0
	v_add_f32_e32 v7, 1.0, v7
	v_div_scale_f32 v8, s[0:1], v7, v7, v6
	v_rcp_f32_e32 v9, v8
	v_div_scale_f32 v10, vcc, v6, v7, v6
	v_fma_f32 v11, -v8, v9, 1.0
	v_fmac_f32_e32 v9, v11, v9
	v_mul_f32_e32 v11, v10, v9
	v_fma_f32 v12, -v8, v11, v10
	v_fmac_f32_e32 v11, v12, v9
	v_fma_f32 v8, -v8, v11, v10
	v_div_fmas_f32 v8, v8, v9, v11
	v_div_fixup_f32 v6, v8, v7, v6
	ds_write_b32 v4, v6
	v_add_u32_e32 v4, 0x800, v4
	s_waitcnt vmcnt(34)
	v_mov_b32_e32 v6, v183
	v_mul_f32_e32 v7, 0xbfb8aa3b, v6
	v_exp_f32_e32 v7, v7
	s_nop 0
	v_add_f32_e32 v7, 1.0, v7
	v_div_scale_f32 v8, s[0:1], v7, v7, v6
	v_rcp_f32_e32 v9, v8
	v_div_scale_f32 v10, vcc, v6, v7, v6
	v_fma_f32 v11, -v8, v9, 1.0
	v_fmac_f32_e32 v9, v11, v9
	v_mul_f32_e32 v11, v10, v9
	v_fma_f32 v12, -v8, v11, v10
	v_fmac_f32_e32 v11, v12, v9
	v_fma_f32 v8, -v8, v11, v10
	v_div_fmas_f32 v8, v8, v9, v11
	v_div_fixup_f32 v6, v8, v7, v6
	ds_write_b32 v4, v6
	v_add_u32_e32 v4, 0x800, v4
	s_waitcnt vmcnt(33)
	v_mov_b32_e32 v6, v184
	v_mul_f32_e32 v7, 0xbfb8aa3b, v6
	v_exp_f32_e32 v7, v7
	s_nop 0
	v_add_f32_e32 v7, 1.0, v7
	v_div_scale_f32 v8, s[0:1], v7, v7, v6
	v_rcp_f32_e32 v9, v8
	v_div_scale_f32 v10, vcc, v6, v7, v6
	v_fma_f32 v11, -v8, v9, 1.0
	v_fmac_f32_e32 v9, v11, v9
	v_mul_f32_e32 v11, v10, v9
	v_fma_f32 v12, -v8, v11, v10
	v_fmac_f32_e32 v11, v12, v9
	v_fma_f32 v8, -v8, v11, v10
	v_div_fmas_f32 v8, v8, v9, v11
	v_div_fixup_f32 v6, v8, v7, v6
	ds_write_b32 v4, v6
	v_add_u32_e32 v4, 0x800, v4
	s_waitcnt vmcnt(32)
	v_mov_b32_e32 v6, v185
	v_mul_f32_e32 v7, 0xbfb8aa3b, v6
	v_exp_f32_e32 v7, v7
	s_nop 0
	v_add_f32_e32 v7, 1.0, v7
	v_div_scale_f32 v8, s[0:1], v7, v7, v6
	v_rcp_f32_e32 v9, v8
	v_div_scale_f32 v10, vcc, v6, v7, v6
	v_fma_f32 v11, -v8, v9, 1.0
	v_fmac_f32_e32 v9, v11, v9
	v_mul_f32_e32 v11, v10, v9
	v_fma_f32 v12, -v8, v11, v10
	v_fmac_f32_e32 v11, v12, v9
	v_fma_f32 v8, -v8, v11, v10
	v_div_fmas_f32 v8, v8, v9, v11
	v_div_fixup_f32 v6, v8, v7, v6
	ds_write_b32 v4, v6
	v_add_u32_e32 v4, 0x800, v4
	s_waitcnt vmcnt(31)
	v_mov_b32_e32 v6, v186
	v_mul_f32_e32 v7, 0xbfb8aa3b, v6
	v_exp_f32_e32 v7, v7
	s_nop 0
	v_add_f32_e32 v7, 1.0, v7
	v_div_scale_f32 v8, s[0:1], v7, v7, v6
	v_rcp_f32_e32 v9, v8
	v_div_scale_f32 v10, vcc, v6, v7, v6
	v_fma_f32 v11, -v8, v9, 1.0
	v_fmac_f32_e32 v9, v11, v9
	v_mul_f32_e32 v11, v10, v9
	v_fma_f32 v12, -v8, v11, v10
	v_fmac_f32_e32 v11, v12, v9
	v_fma_f32 v8, -v8, v11, v10
	v_div_fmas_f32 v8, v8, v9, v11
	v_div_fixup_f32 v6, v8, v7, v6
	ds_write_b32 v4, v6
	v_add_u32_e32 v4, 0x800, v4
	s_waitcnt vmcnt(30)
; __device__ __forceinline__ void phase0(const Params& p, char* shm) {
;     ...
;         for (int i = tid; i < 9 * 2048; i += 512) { const int r = i >> 11, k = i & 2047; const float v = r < 8 ? p.in[1][r * 2048 + k] : p.in[3][k]; condS[i] = v / (1.f + __expf(-v)); }
	v_mov_b32_e32 v6, v187
	v_mul_f32_e32 v7, 0xbfb8aa3b, v6
	v_exp_f32_e32 v7, v7
	s_nop 0
	v_add_f32_e32 v7, 1.0, v7
	v_div_scale_f32 v8, s[0:1], v7, v7, v6
	v_rcp_f32_e32 v9, v8
	v_div_scale_f32 v10, vcc, v6, v7, v6
	v_fma_f32 v11, -v8, v9, 1.0
	v_fmac_f32_e32 v9, v11, v9
	v_mul_f32_e32 v11, v10, v9
	v_fma_f32 v12, -v8, v11, v10
	v_fmac_f32_e32 v11, v12, v9
	v_fma_f32 v8, -v8, v11, v10
	v_div_fmas_f32 v8, v8, v9, v11
	v_div_fixup_f32 v6, v8, v7, v6
	ds_write_b32 v4, v6
	v_add_u32_e32 v4, 0x800, v4
	s_waitcnt vmcnt(29)
	v_mov_b32_e32 v6, v188
	v_mul_f32_e32 v7, 0xbfb8aa3b, v6
	v_exp_f32_e32 v7, v7
	s_nop 0
	v_add_f32_e32 v7, 1.0, v7
	v_div_scale_f32 v8, s[0:1], v7, v7, v6
	v_rcp_f32_e32 v9, v8
	v_div_scale_f32 v10, vcc, v6, v7, v6
	v_fma_f32 v11, -v8, v9, 1.0
	v_fmac_f32_e32 v9, v11, v9
	v_mul_f32_e32 v11, v10, v9
	v_fma_f32 v12, -v8, v11, v10
	v_fmac_f32_e32 v11, v12, v9
	v_fma_f32 v8, -v8, v11, v10
	v_div_fmas_f32 v8, v8, v9, v11
	v_div_fixup_f32 v6, v8, v7, v6
	ds_write_b32 v4, v6
	v_add_u32_e32 v4, 0x800, v4
	s_waitcnt vmcnt(28)
	v_mov_b32_e32 v6, v189
	v_mul_f32_e32 v7, 0xbfb8aa3b, v6
	v_exp_f32_e32 v7, v7
	s_nop 0
	v_add_f32_e32 v7, 1.0, v7
	v_div_scale_f32 v8, s[0:1], v7, v7, v6
	v_rcp_f32_e32 v9, v8
	v_div_scale_f32 v10, vcc, v6, v7, v6
	v_fma_f32 v11, -v8, v9, 1.0
	v_fmac_f32_e32 v9, v11, v9
	v_mul_f32_e32 v11, v10, v9
	v_fma_f32 v12, -v8, v11, v10
	v_fmac_f32_e32 v11, v12, v9
	v_fma_f32 v8, -v8, v11, v10
	v_div_fmas_f32 v8, v8, v9, v11
	v_div_fixup_f32 v6, v8, v7, v6
	ds_write_b32 v4, v6
	v_add_u32_e32 v4, 0x800, v4
	s_waitcnt vmcnt(27)
	v_mov_b32_e32 v6, v190
	v_mul_f32_e32 v7, 0xbfb8aa3b, v6
	v_exp_f32_e32 v7, v7
	s_nop 0
	v_add_f32_e32 v7, 1.0, v7
	v_div_scale_f32 v8, s[0:1], v7, v7, v6
	v_rcp_f32_e32 v9, v8
	v_div_scale_f32 v10, vcc, v6, v7, v6
	v_fma_f32 v11, -v8, v9, 1.0
	v_fmac_f32_e32 v9, v11, v9
	v_mul_f32_e32 v11, v10, v9
	v_fma_f32 v12, -v8, v11, v10
	v_fmac_f32_e32 v11, v12, v9
	v_fma_f32 v8, -v8, v11, v10
	v_div_fmas_f32 v8, v8, v9, v11
	v_div_fixup_f32 v6, v8, v7, v6
	ds_write_b32 v4, v6
	v_add_u32_e32 v4, 0x800, v4
	s_waitcnt vmcnt(26)
	v_mov_b32_e32 v6, v191
	v_mul_f32_e32 v7, 0xbfb8aa3b, v6
	v_exp_f32_e32 v7, v7
	s_nop 0
	v_add_f32_e32 v7, 1.0, v7
	v_div_scale_f32 v8, s[0:1], v7, v7, v6
	v_rcp_f32_e32 v9, v8
	v_div_scale_f32 v10, vcc, v6, v7, v6
	v_fma_f32 v11, -v8, v9, 1.0
	v_fmac_f32_e32 v9, v11, v9
	v_mul_f32_e32 v11, v10, v9
	v_fma_f32 v12, -v8, v11, v10
	v_fmac_f32_e32 v11, v12, v9
	v_fma_f32 v8, -v8, v11, v10
	v_div_fmas_f32 v8, v8, v9, v11
	v_div_fixup_f32 v6, v8, v7, v6
	ds_write_b32 v4, v6
	v_add_u32_e32 v4, 0x800, v4
	s_waitcnt vmcnt(25)
	v_mov_b32_e32 v6, v192
	v_mul_f32_e32 v7, 0xbfb8aa3b, v6
	v_exp_f32_e32 v7, v7
	s_nop 0
	v_add_f32_e32 v7, 1.0, v7
	v_div_scale_f32 v8, s[0:1], v7, v7, v6
	v_rcp_f32_e32 v9, v8
	v_div_scale_f32 v10, vcc, v6, v7, v6
	v_fma_f32 v11, -v8, v9, 1.0
	v_fmac_f32_e32 v9, v11, v9
	v_mul_f32_e32 v11, v10, v9
	v_fma_f32 v12, -v8, v11, v10
	v_fmac_f32_e32 v11, v12, v9
	v_fma_f32 v8, -v8, v11, v10
	v_div_fmas_f32 v8, v8, v9, v11
	v_div_fixup_f32 v6, v8, v7, v6
	ds_write_b32 v4, v6
	v_add_u32_e32 v4, 0x800, v4
	s_waitcnt vmcnt(24)
	v_mov_b32_e32 v6, v193
	v_mul_f32_e32 v7, 0xbfb8aa3b, v6
	v_exp_f32_e32 v7, v7
	s_nop 0
	v_add_f32_e32 v7, 1.0, v7
	v_div_scale_f32 v8, s[0:1], v7, v7, v6
	v_rcp_f32_e32 v9, v8
	v_div_scale_f32 v10, vcc, v6, v7, v6
	v_fma_f32 v11, -v8, v9, 1.0
	v_fmac_f32_e32 v9, v11, v9
	v_mul_f32_e32 v11, v10, v9
	v_fma_f32 v12, -v8, v11, v10
	v_fmac_f32_e32 v11, v12, v9
	v_fma_f32 v8, -v8, v11, v10
	v_div_fmas_f32 v8, v8, v9, v11
	v_div_fixup_f32 v6, v8, v7, v6
	ds_write_b32 v4, v6
	v_add_u32_e32 v4, 0x800, v4
	s_waitcnt vmcnt(23)
	v_mov_b32_e32 v6, v194
	v_mul_f32_e32 v7, 0xbfb8aa3b, v6
	v_exp_f32_e32 v7, v7
	s_nop 0
	v_add_f32_e32 v7, 1.0, v7
	v_div_scale_f32 v8, s[0:1], v7, v7, v6
	v_rcp_f32_e32 v9, v8
	v_div_scale_f32 v10, vcc, v6, v7, v6
	v_fma_f32 v11, -v8, v9, 1.0
	v_fmac_f32_e32 v9, v11, v9
	v_mul_f32_e32 v11, v10, v9
	v_fma_f32 v12, -v8, v11, v10
	v_fmac_f32_e32 v11, v12, v9
	v_fma_f32 v8, -v8, v11, v10
	v_div_fmas_f32 v8, v8, v9, v11
	v_div_fixup_f32 v6, v8, v7, v6
	ds_write_b32 v4, v6
	v_add_u32_e32 v4, 0x800, v4
	s_waitcnt vmcnt(22)
	v_mov_b32_e32 v6, v195
	v_mul_f32_e32 v7, 0xbfb8aa3b, v6
	v_exp_f32_e32 v7, v7
	s_nop 0
	v_add_f32_e32 v7, 1.0, v7
	v_div_scale_f32 v8, s[0:1], v7, v7, v6
	v_rcp_f32_e32 v9, v8
	v_div_scale_f32 v10, vcc, v6, v7, v6
	v_fma_f32 v11, -v8, v9, 1.0
	v_fmac_f32_e32 v9, v11, v9
	v_mul_f32_e32 v11, v10, v9
	v_fma_f32 v12, -v8, v11, v10
	v_fmac_f32_e32 v11, v12, v9
	v_fma_f32 v8, -v8, v11, v10
	v_div_fmas_f32 v8, v8, v9, v11
	v_div_fixup_f32 v6, v8, v7, v6
	ds_write_b32 v4, v6
	v_add_u32_e32 v4, 0x800, v4
	s_waitcnt vmcnt(21)
	v_mov_b32_e32 v6, v196
	v_mul_f32_e32 v7, 0xbfb8aa3b, v6
	v_exp_f32_e32 v7, v7
	s_nop 0
	v_add_f32_e32 v7, 1.0, v7
	v_div_scale_f32 v8, s[0:1], v7, v7, v6
	v_rcp_f32_e32 v9, v8
	v_div_scale_f32 v10, vcc, v6, v7, v6
	v_fma_f32 v11, -v8, v9, 1.0
	v_fmac_f32_e32 v9, v11, v9
	v_mul_f32_e32 v11, v10, v9
	v_fma_f32 v12, -v8, v11, v10
	v_fmac_f32_e32 v11, v12, v9
	v_fma_f32 v8, -v8, v11, v10
	v_div_fmas_f32 v8, v8, v9, v11
	v_div_fixup_f32 v6, v8, v7, v6
	ds_write_b32 v4, v6
	v_add_u32_e32 v4, 0x800, v4
	s_waitcnt vmcnt(20)
	v_mov_b32_e32 v6, v197
	v_mul_f32_e32 v7, 0xbfb8aa3b, v6
	v_exp_f32_e32 v7, v7
	s_nop 0
	v_add_f32_e32 v7, 1.0, v7
	v_div_scale_f32 v8, s[0:1], v7, v7, v6
	v_rcp_f32_e32 v9, v8
	v_div_scale_f32 v10, vcc, v6, v7, v6
	v_fma_f32 v11, -v8, v9, 1.0
	v_fmac_f32_e32 v9, v11, v9
	v_mul_f32_e32 v11, v10, v9
	v_fma_f32 v12, -v8, v11, v10
	v_fmac_f32_e32 v11, v12, v9
	v_fma_f32 v8, -v8, v11, v10
	v_div_fmas_f32 v8, v8, v9, v11
	v_div_fixup_f32 v6, v8, v7, v6
	ds_write_b32 v4, v6
	v_add_u32_e32 v4, 0x800, v4
	s_waitcnt vmcnt(19)
; __device__ __forceinline__ void phase0(const Params& p, char* shm) {
;     ...
;         for (int i = tid; i < 9 * 2048; i += 512) { const int r = i >> 11, k = i & 2047; const float v = r < 8 ? p.in[1][r * 2048 + k] : p.in[3][k]; condS[i] = v / (1.f + __expf(-v)); }
	v_mov_b32_e32 v6, v198
	v_mul_f32_e32 v7, 0xbfb8aa3b, v6
	v_exp_f32_e32 v7, v7
	s_nop 0
	v_add_f32_e32 v7, 1.0, v7
	v_div_scale_f32 v8, s[0:1], v7, v7, v6
	v_rcp_f32_e32 v9, v8
	v_div_scale_f32 v10, vcc, v6, v7, v6
	v_fma_f32 v11, -v8, v9, 1.0
	v_fmac_f32_e32 v9, v11, v9
	v_mul_f32_e32 v11, v10, v9
	v_fma_f32 v12, -v8, v11, v10
	v_fmac_f32_e32 v11, v12, v9
	v_fma_f32 v8, -v8, v11, v10
	v_div_fmas_f32 v8, v8, v9, v11
	v_div_fixup_f32 v6, v8, v7, v6
	ds_write_b32 v4, v6
	v_add_u32_e32 v4, 0x800, v4
	s_waitcnt vmcnt(18)
	v_mov_b32_e32 v6, v199
	v_mul_f32_e32 v7, 0xbfb8aa3b, v6
	v_exp_f32_e32 v7, v7
	s_nop 0
	v_add_f32_e32 v7, 1.0, v7
	v_div_scale_f32 v8, s[0:1], v7, v7, v6
	v_rcp_f32_e32 v9, v8
	v_div_scale_f32 v10, vcc, v6, v7, v6
	v_fma_f32 v11, -v8, v9, 1.0
	v_fmac_f32_e32 v9, v11, v9
	v_mul_f32_e32 v11, v10, v9
	v_fma_f32 v12, -v8, v11, v10
	v_fmac_f32_e32 v11, v12, v9
	v_fma_f32 v8, -v8, v11, v10
	v_div_fmas_f32 v8, v8, v9, v11
	v_div_fixup_f32 v6, v8, v7, v6
	ds_write_b32 v4, v6
	v_add_u32_e32 v4, 0x800, v4
	s_waitcnt vmcnt(17)
	v_mov_b32_e32 v6, v200
	v_mul_f32_e32 v7, 0xbfb8aa3b, v6
	v_exp_f32_e32 v7, v7
	s_nop 0
	v_add_f32_e32 v7, 1.0, v7
	v_div_scale_f32 v8, s[0:1], v7, v7, v6
	v_rcp_f32_e32 v9, v8
	v_div_scale_f32 v10, vcc, v6, v7, v6
	v_fma_f32 v11, -v8, v9, 1.0
	v_fmac_f32_e32 v9, v11, v9
	v_mul_f32_e32 v11, v10, v9
	v_fma_f32 v12, -v8, v11, v10
	v_fmac_f32_e32 v11, v12, v9
	v_fma_f32 v8, -v8, v11, v10
	v_div_fmas_f32 v8, v8, v9, v11
	v_div_fixup_f32 v6, v8, v7, v6
	ds_write_b32 v4, v6
	v_add_u32_e32 v4, 0x800, v4
	s_waitcnt vmcnt(16)
	v_mov_b32_e32 v6, v201
	v_mul_f32_e32 v7, 0xbfb8aa3b, v6
	v_exp_f32_e32 v7, v7
	s_nop 0
	v_add_f32_e32 v7, 1.0, v7
	v_div_scale_f32 v8, s[0:1], v7, v7, v6
	v_rcp_f32_e32 v9, v8
	v_div_scale_f32 v10, vcc, v6, v7, v6
	v_fma_f32 v11, -v8, v9, 1.0
	v_fmac_f32_e32 v9, v11, v9
	v_mul_f32_e32 v11, v10, v9
	v_fma_f32 v12, -v8, v11, v10
	v_fmac_f32_e32 v11, v12, v9
	v_fma_f32 v8, -v8, v11, v10
	v_div_fmas_f32 v8, v8, v9, v11
	v_div_fixup_f32 v6, v8, v7, v6
	ds_write_b32 v4, v6
	v_add_u32_e32 v4, 0x800, v4
	s_waitcnt vmcnt(15)
	v_mov_b32_e32 v6, v202
	v_mul_f32_e32 v7, 0xbfb8aa3b, v6
	v_exp_f32_e32 v7, v7
	s_nop 0
	v_add_f32_e32 v7, 1.0, v7
	v_div_scale_f32 v8, s[0:1], v7, v7, v6
	v_rcp_f32_e32 v9, v8
	v_div_scale_f32 v10, vcc, v6, v7, v6
	v_fma_f32 v11, -v8, v9, 1.0
	v_fmac_f32_e32 v9, v11, v9
	v_mul_f32_e32 v11, v10, v9
	v_fma_f32 v12, -v8, v11, v10
	v_fmac_f32_e32 v11, v12, v9
	v_fma_f32 v8, -v8, v11, v10
	v_div_fmas_f32 v8, v8, v9, v11
	v_div_fixup_f32 v6, v8, v7, v6
	ds_write_b32 v4, v6
	v_add_u32_e32 v4, 0x800, v4
	s_waitcnt vmcnt(14)
	v_mov_b32_e32 v6, v203
	v_mul_f32_e32 v7, 0xbfb8aa3b, v6
	v_exp_f32_e32 v7, v7
	s_nop 0
	v_add_f32_e32 v7, 1.0, v7
	v_div_scale_f32 v8, s[0:1], v7, v7, v6
	v_rcp_f32_e32 v9, v8
	v_div_scale_f32 v10, vcc, v6, v7, v6
	v_fma_f32 v11, -v8, v9, 1.0
	v_fmac_f32_e32 v9, v11, v9
	v_mul_f32_e32 v11, v10, v9
	v_fma_f32 v12, -v8, v11, v10
	v_fmac_f32_e32 v11, v12, v9
	v_fma_f32 v8, -v8, v11, v10
	v_div_fmas_f32 v8, v8, v9, v11
	v_div_fixup_f32 v6, v8, v7, v6
	ds_write_b32 v4, v6
	v_add_u32_e32 v4, 0x800, v4
	s_waitcnt vmcnt(13)
	v_mov_b32_e32 v6, v204
	v_mul_f32_e32 v7, 0xbfb8aa3b, v6
	v_exp_f32_e32 v7, v7
	s_nop 0
	v_add_f32_e32 v7, 1.0, v7
	v_div_scale_f32 v8, s[0:1], v7, v7, v6
	v_rcp_f32_e32 v9, v8
	v_div_scale_f32 v10, vcc, v6, v7, v6
	v_fma_f32 v11, -v8, v9, 1.0
	v_fmac_f32_e32 v9, v11, v9
	v_mul_f32_e32 v11, v10, v9
	v_fma_f32 v12, -v8, v11, v10
	v_fmac_f32_e32 v11, v12, v9
	v_fma_f32 v8, -v8, v11, v10
	v_div_fmas_f32 v8, v8, v9, v11
	v_div_fixup_f32 v6, v8, v7, v6
	ds_write_b32 v4, v6
	v_add_u32_e32 v4, 0x800, v4
	s_waitcnt vmcnt(12)
	v_mov_b32_e32 v6, v205
	v_mul_f32_e32 v7, 0xbfb8aa3b, v6
	v_exp_f32_e32 v7, v7
	s_nop 0
	v_add_f32_e32 v7, 1.0, v7
	v_div_scale_f32 v8, s[0:1], v7, v7, v6
	v_rcp_f32_e32 v9, v8
	v_div_scale_f32 v10, vcc, v6, v7, v6
	v_fma_f32 v11, -v8, v9, 1.0
	v_fmac_f32_e32 v9, v11, v9
	v_mul_f32_e32 v11, v10, v9
	v_fma_f32 v12, -v8, v11, v10
	v_fmac_f32_e32 v11, v12, v9
	v_fma_f32 v8, -v8, v11, v10
	v_div_fmas_f32 v8, v8, v9, v11
	v_div_fixup_f32 v6, v8, v7, v6
	ds_write_b32 v4, v6
	v_add_u32_e32 v4, 0x800, v4
	s_waitcnt vmcnt(11)
	v_mov_b32_e32 v6, v206
	v_mul_f32_e32 v7, 0xbfb8aa3b, v6
	v_exp_f32_e32 v7, v7
	s_nop 0
	v_add_f32_e32 v7, 1.0, v7
	v_div_scale_f32 v8, s[0:1], v7, v7, v6
	v_rcp_f32_e32 v9, v8
	v_div_scale_f32 v10, vcc, v6, v7, v6
	v_fma_f32 v11, -v8, v9, 1.0
	v_fmac_f32_e32 v9, v11, v9
	v_mul_f32_e32 v11, v10, v9
	v_fma_f32 v12, -v8, v11, v10
	v_fmac_f32_e32 v11, v12, v9
	v_fma_f32 v8, -v8, v11, v10
	v_div_fmas_f32 v8, v8, v9, v11
	v_div_fixup_f32 v6, v8, v7, v6
	ds_write_b32 v4, v6
	v_add_u32_e32 v4, 0x800, v4
	s_waitcnt vmcnt(10)
	v_mov_b32_e32 v6, v207
	v_mul_f32_e32 v7, 0xbfb8aa3b, v6
	v_exp_f32_e32 v7, v7
	s_nop 0
	v_add_f32_e32 v7, 1.0, v7
	v_div_scale_f32 v8, s[0:1], v7, v7, v6
	v_rcp_f32_e32 v9, v8
	v_div_scale_f32 v10, vcc, v6, v7, v6
	v_fma_f32 v11, -v8, v9, 1.0
	v_fmac_f32_e32 v9, v11, v9
	v_mul_f32_e32 v11, v10, v9
	v_fma_f32 v12, -v8, v11, v10
	v_fmac_f32_e32 v11, v12, v9
	v_fma_f32 v8, -v8, v11, v10
	v_div_fmas_f32 v8, v8, v9, v11
	v_div_fixup_f32 v6, v8, v7, v6
	ds_write_b32 v4, v6
	v_add_u32_e32 v4, 0x800, v4
	s_waitcnt vmcnt(9)
; __device__ __forceinline__ void phase0(const Params& p, char* shm) {
;     ...
;         for (int i = tid; i < 9 * 2048; i += 512) { const int r = i >> 11, k = i & 2047; const float v = r < 8 ? p.in[1][r * 2048 + k] : p.in[3][k]; condS[i] = v / (1.f + __expf(-v)); }
;     ...
;         __syncthreads();
	v_mov_b32_e32 v6, v208
	v_mul_f32_e32 v7, 0xbfb8aa3b, v6
	v_exp_f32_e32 v7, v7
	s_nop 0
	v_add_f32_e32 v7, 1.0, v7
	v_div_scale_f32 v8, s[0:1], v7, v7, v6
	v_rcp_f32_e32 v9, v8
	v_div_scale_f32 v10, vcc, v6, v7, v6
	v_fma_f32 v11, -v8, v9, 1.0
	v_fmac_f32_e32 v9, v11, v9
	v_mul_f32_e32 v11, v10, v9
	v_fma_f32 v12, -v8, v11, v10
	v_fmac_f32_e32 v11, v12, v9
	v_fma_f32 v8, -v8, v11, v10
	v_div_fmas_f32 v8, v8, v9, v11
	v_div_fixup_f32 v6, v8, v7, v6
	ds_write_b32 v4, v6
	v_add_u32_e32 v4, 0x800, v4
	s_waitcnt vmcnt(8)
	v_mov_b32_e32 v6, v209
	v_mul_f32_e32 v7, 0xbfb8aa3b, v6
	v_exp_f32_e32 v7, v7
	s_nop 0
	v_add_f32_e32 v7, 1.0, v7
	v_div_scale_f32 v8, s[0:1], v7, v7, v6
	v_rcp_f32_e32 v9, v8
	v_div_scale_f32 v10, vcc, v6, v7, v6
	v_fma_f32 v11, -v8, v9, 1.0
	v_fmac_f32_e32 v9, v11, v9
	v_mul_f32_e32 v11, v10, v9
	v_fma_f32 v12, -v8, v11, v10
	v_fmac_f32_e32 v11, v12, v9
	v_fma_f32 v8, -v8, v11, v10
	v_div_fmas_f32 v8, v8, v9, v11
	v_div_fixup_f32 v6, v8, v7, v6
	ds_write_b32 v4, v6
	v_add_u32_e32 v4, 0x800, v4
	s_waitcnt vmcnt(7)
	v_mov_b32_e32 v6, v210
	v_mul_f32_e32 v7, 0xbfb8aa3b, v6
	v_exp_f32_e32 v7, v7
	s_nop 0
	v_add_f32_e32 v7, 1.0, v7
	v_div_scale_f32 v8, s[0:1], v7, v7, v6
	v_rcp_f32_e32 v9, v8
	v_div_scale_f32 v10, vcc, v6, v7, v6
	v_fma_f32 v11, -v8, v9, 1.0
	v_fmac_f32_e32 v9, v11, v9
	v_mul_f32_e32 v11, v10, v9
	v_fma_f32 v12, -v8, v11, v10
	v_fmac_f32_e32 v11, v12, v9
	v_fma_f32 v8, -v8, v11, v10
	v_div_fmas_f32 v8, v8, v9, v11
	v_div_fixup_f32 v6, v8, v7, v6
	ds_write_b32 v4, v6
	v_add_u32_e32 v4, 0x800, v4
	s_waitcnt vmcnt(6)
	v_mov_b32_e32 v6, v211
	v_mul_f32_e32 v7, 0xbfb8aa3b, v6
	v_exp_f32_e32 v7, v7
	s_nop 0
	v_add_f32_e32 v7, 1.0, v7
	v_div_scale_f32 v8, s[0:1], v7, v7, v6
	v_rcp_f32_e32 v9, v8
	v_div_scale_f32 v10, vcc, v6, v7, v6
	v_fma_f32 v11, -v8, v9, 1.0
	v_fmac_f32_e32 v9, v11, v9
	v_mul_f32_e32 v11, v10, v9
	v_fma_f32 v12, -v8, v11, v10
	v_fmac_f32_e32 v11, v12, v9
	v_fma_f32 v8, -v8, v11, v10
	v_div_fmas_f32 v8, v8, v9, v11
	v_div_fixup_f32 v6, v8, v7, v6
	ds_write_b32 v4, v6
	v_add_u32_e32 v4, 0x800, v4
	s_waitcnt vmcnt(5)
	v_mov_b32_e32 v6, v212
	v_mul_f32_e32 v7, 0xbfb8aa3b, v6
	v_exp_f32_e32 v7, v7
	s_nop 0
	v_add_f32_e32 v7, 1.0, v7
	v_div_scale_f32 v8, s[0:1], v7, v7, v6
	v_rcp_f32_e32 v9, v8
	v_div_scale_f32 v10, vcc, v6, v7, v6
	v_fma_f32 v11, -v8, v9, 1.0
	v_fmac_f32_e32 v9, v11, v9
	v_mul_f32_e32 v11, v10, v9
	v_fma_f32 v12, -v8, v11, v10
	v_fmac_f32_e32 v11, v12, v9
	v_fma_f32 v8, -v8, v11, v10
	v_div_fmas_f32 v8, v8, v9, v11
	v_div_fixup_f32 v6, v8, v7, v6
	ds_write_b32 v4, v6
	v_add_u32_e32 v4, 0x800, v4
	s_waitcnt vmcnt(4)
	v_mov_b32_e32 v6, v213
	v_mul_f32_e32 v7, 0xbfb8aa3b, v6
	v_exp_f32_e32 v7, v7
	s_nop 0
	v_add_f32_e32 v7, 1.0, v7
	v_div_scale_f32 v8, s[0:1], v7, v7, v6
	v_rcp_f32_e32 v9, v8
	v_div_scale_f32 v10, vcc, v6, v7, v6
	v_fma_f32 v11, -v8, v9, 1.0
	v_fmac_f32_e32 v9, v11, v9
	v_mul_f32_e32 v11, v10, v9
	v_fma_f32 v12, -v8, v11, v10
	v_fmac_f32_e32 v11, v12, v9
	v_fma_f32 v8, -v8, v11, v10
	v_div_fmas_f32 v8, v8, v9, v11
	v_div_fixup_f32 v6, v8, v7, v6
	ds_write_b32 v4, v6
	v_add_u32_e32 v4, 0x800, v4
	s_waitcnt vmcnt(3)
	v_mov_b32_e32 v6, v214
	v_mul_f32_e32 v7, 0xbfb8aa3b, v6
	v_exp_f32_e32 v7, v7
	s_nop 0
	v_add_f32_e32 v7, 1.0, v7
	v_div_scale_f32 v8, s[0:1], v7, v7, v6
	v_rcp_f32_e32 v9, v8
	v_div_scale_f32 v10, vcc, v6, v7, v6
	v_fma_f32 v11, -v8, v9, 1.0
	v_fmac_f32_e32 v9, v11, v9
	v_mul_f32_e32 v11, v10, v9
	v_fma_f32 v12, -v8, v11, v10
	v_fmac_f32_e32 v11, v12, v9
	v_fma_f32 v8, -v8, v11, v10
	v_div_fmas_f32 v8, v8, v9, v11
	v_div_fixup_f32 v6, v8, v7, v6
	ds_write_b32 v4, v6
	v_add_u32_e32 v4, 0x800, v4
	s_waitcnt vmcnt(2)
	v_mov_b32_e32 v6, v215
	v_mul_f32_e32 v7, 0xbfb8aa3b, v6
	v_exp_f32_e32 v7, v7
	s_nop 0
	v_add_f32_e32 v7, 1.0, v7
	v_div_scale_f32 v8, s[0:1], v7, v7, v6
	v_rcp_f32_e32 v9, v8
	v_div_scale_f32 v10, vcc, v6, v7, v6
	v_fma_f32 v11, -v8, v9, 1.0
	v_fmac_f32_e32 v9, v11, v9
	v_mul_f32_e32 v11, v10, v9
	v_fma_f32 v12, -v8, v11, v10
	v_fmac_f32_e32 v11, v12, v9
	v_fma_f32 v8, -v8, v11, v10
	v_div_fmas_f32 v8, v8, v9, v11
	v_div_fixup_f32 v6, v8, v7, v6
	ds_write_b32 v4, v6
	v_add_u32_e32 v4, 0x800, v4
	s_waitcnt vmcnt(1)
	v_mov_b32_e32 v6, v216
	v_mul_f32_e32 v7, 0xbfb8aa3b, v6
	v_exp_f32_e32 v7, v7
	s_nop 0
	v_add_f32_e32 v7, 1.0, v7
	v_div_scale_f32 v8, s[0:1], v7, v7, v6
	v_rcp_f32_e32 v9, v8
	v_div_scale_f32 v10, vcc, v6, v7, v6
	v_fma_f32 v11, -v8, v9, 1.0
	v_fmac_f32_e32 v9, v11, v9
	v_mul_f32_e32 v11, v10, v9
	v_fma_f32 v12, -v8, v11, v10
	v_fmac_f32_e32 v11, v12, v9
	v_fma_f32 v8, -v8, v11, v10
	v_div_fmas_f32 v8, v8, v9, v11
	v_div_fixup_f32 v6, v8, v7, v6
	ds_write_b32 v4, v6
	v_add_u32_e32 v4, 0x800, v4
	s_waitcnt vmcnt(0)
	v_mov_b32_e32 v6, v217
	v_mul_f32_e32 v7, 0xbfb8aa3b, v6
	v_exp_f32_e32 v7, v7
	s_nop 0
	v_add_f32_e32 v7, 1.0, v7
	v_div_scale_f32 v8, s[0:1], v7, v7, v6
	v_rcp_f32_e32 v9, v8
	v_div_scale_f32 v10, vcc, v6, v7, v6
	v_fma_f32 v11, -v8, v9, 1.0
	v_fmac_f32_e32 v9, v11, v9
	v_mul_f32_e32 v11, v10, v9
	v_fma_f32 v12, -v8, v11, v10
	v_fmac_f32_e32 v11, v12, v9
	v_fma_f32 v8, -v8, v11, v10
	v_div_fmas_f32 v8, v8, v9, v11
	v_div_fixup_f32 v6, v8, v7, v6
	ds_write_b32 v4, v6
	v_add_u32_e32 v4, 0x800, v4
